# attention item prologue: first two K/V tiles' global loads issued before the wait for Q (own address computation), on top of the SrcC-fold loop
# baseline (speedup 1.0000x reference)
; DI float bflo(unsigned u) { return __uint_as_float(u << 16); }
; DI float bfhi(unsigned u) { return __uint_as_float(u & 0xffff0000u); }
; DI f32x16 zero16() { f32x16 z; for (int i = 0; i < 16; ++i) z[i] = 0.f; return z; }
; DI void phase_attn(const Params& p, int hf, bool skipctx, char* smem, int& rot) {
;     ...
;       for (int ks = 0; ks < 6; ++ks) qu[ks] = *(const uint4*)(Qb + tq * 768 + head * 96 + ks * 16 + h * 8);
; #pragma unroll
;       for (int ks = 0; ks < 4; ++ks) {
;         const uint4 u = qu[ks];
;         qf[ks] = pack8(bflo(u.x) * QSCALE, bfhi(u.x) * QSCALE, bflo(u.y) * QSCALE, bfhi(u.y) * QSCALE, bflo(u.z) * QSCALE, bfhi(u.z) * QSCALE, bflo(u.w) * QSCALE, bfhi(u.w) * QSCALE);
;       }
;       const unsigned a1[4] = {qu[4].x, qu[4].y, qu[4].z, qu[4].w}, a2[4] = {qu[5].x, qu[5].y, qu[5].z, qu[5].w};
;       float o1[8], o2[8];
;       const int sq_ = s0 + w * 32 + r;
; #pragma unroll
;       for (int e = 0; e < 8; ++e) {
;         const float x1 = ((e & 1) ? bfhi(a1[e >> 1]) : bflo(a1[e >> 1])) * QSCALE;
;         const float x2 = ((e & 1) ? bfhi(a2[e >> 1]) : bflo(a2[e >> 1])) * QSCALE;
;         float cs = 1.f, sn = 0.f;
;         if (sq_ >= LC) { cs = axc[(sq_ - LC) * 16 + 8 * h + e]; sn = axs[(sq_ - LC) * 16 + 8 * h + e]; }
;         o1[e] = x1 * cs - x2 * sn; o2[e] = x1 * sn + x2 * cs;
;       }
;       qf[4] = pack8(o1[0], o1[1], o1[2], o1[3], o1[4], o1[5], o1[6], o1[7]);
;       qf[5] = pack8(o2[0], o2[1], o2[2], o2[3], o2[4], o2[5], o2[6], o2[7]);
;     }
;     const bf16_t* Kg = Kb + (size_t)(bl * 8 + head) * S * 96;
;     const bf16_t* Vg = VTb + (size_t)(bl * 8 + head) * 64 * S;
;     f32x16 o[2]; o[0] = zero16(); o[1] = zero16();
;     float m_run = -1e30f, l_run = 0.f;
;     uint4 ak0, ak1, ak2, av0, av1, bk0, bk1, bk2, bv0, bv1;
;     const int kr0 = tid / 12, kc0 = tid - kr0 * 12, kr1 = (tid + 512) / 12, kc1 = (tid + 512) - kr1 * 12, kr2 = (tid + 1024) / 12, kc2 = (tid + 1024) - kr2 * 12;
;     const int vr0 = tid >> 4, vr1 = (tid + 512) >> 4, vc = tid & 15;
.LBB0_794:
	s_or_b64 exec, exec, s[26:27]
	v_mov_b32_e32 v128, s4
	v_mov_b32_e32 v129, 0xcc000
	v_mov_b32_e32 v130, s90
	v_mov_b32_e32 v131, s91
	v_readlane_b32 s100, v252, 5
	v_readlane_b32 s101, v252, 6
	v_mad_u64_u32 v[132:133], vcc, v128, v129, v[130:131]
	v_mov_b32_e32 v129, 0x88000
	v_mov_b32_e32 v157, 0
	v_mov_b32_e32 v130, s100
	v_mov_b32_e32 v131, s101
	v_mov_b32_e32 v138, 0x2aaaaaab
	v_mad_u64_u32 v[134:135], vcc, v128, v129, v[130:131]
	v_mov_b32_e32 v136, v160
	v_mul_hi_u32 v137, v136, v138
	v_lshrrev_b32_e32 v137, 1, v137
	v_mul_u32_u24_e32 v139, 12, v137
	v_sub_u32_e32 v139, v136, v139
	v_mul_u32_u24_e32 v137, 0xc0, v137
	v_lshl_add_u32 v156, v139, 4, v137
	v_lshl_add_u64 v[140:141], v[132:133], 0, v[156:157]
	v_add_u32_e32 v136, 0x200, v160
	v_mul_hi_u32 v137, v136, v138
	v_lshrrev_b32_e32 v137, 1, v137
	v_mul_u32_u24_e32 v139, 12, v137
	v_sub_u32_e32 v139, v136, v139
	v_mul_u32_u24_e32 v137, 0xc0, v137
	v_lshl_add_u32 v156, v139, 4, v137
	v_lshl_add_u64 v[142:143], v[132:133], 0, v[156:157]
	v_add_u32_e32 v136, 0x400, v160
	v_mul_hi_u32 v137, v136, v138
	v_lshrrev_b32_e32 v137, 1, v137
	v_mul_u32_u24_e32 v139, 12, v137
	v_sub_u32_e32 v139, v136, v139
	v_mul_u32_u24_e32 v137, 0xc0, v137
	v_lshl_add_u32 v156, v139, 4, v137
	v_lshl_add_u64 v[144:145], v[132:133], 0, v[156:157]
	v_lshrrev_b32_e32 v136, 4, v160
	v_and_b32_e32 v139, 15, v160
	v_lshlrev_b32_e32 v139, 4, v139
	v_mov_b32_e32 v137, 0x2200
	v_mad_u32_u24 v156, v136, v137, v139
	v_lshl_add_u64 v[146:147], v[134:135], 0, v[156:157]
	v_mov_b32_e32 v156, 0x44000
	v_lshl_add_u64 v[148:149], v[146:147], 0, v[156:157]
	global_load_dwordx4 v[76:79], v[140:141], off
	global_load_dwordx4 v[80:83], v[142:143], off
	global_load_dwordx4 v[84:87], v[144:145], off
	global_load_dwordx4 v[92:95], v[146:147], off
	global_load_dwordx4 v[104:107], v[148:149], off
	v_mov_b32_e32 v156, 0x6000
	v_lshl_add_u64 v[150:151], v[142:143], 0, v[156:157]
	v_lshl_add_u64 v[152:153], v[144:145], 0, v[156:157]
	v_lshl_add_u64 v[154:155], v[140:141], 0, v[156:157]
	global_load_dwordx4 v[108:111], v[150:151], off
	global_load_dwordx4 v[116:119], v[152:153], off
	global_load_dwordx4 v[120:123], v[146:147], off offset:256
	global_load_dwordx4 v[112:115], v[154:155], off
	global_load_dwordx4 v[124:127], v[148:149], off offset:256
	s_waitcnt vmcnt(10)
	v_lshlrev_b32_e32 v27, 16, v23
	v_lshlrev_b32_e32 v26, 16, v19
	v_pk_mul_f32 v[26:27], v[26:27], s[48:49] op_sel_hi:[1,0]
	v_lshlrev_b32_e32 v47, 16, v22
	v_pk_mul_f32 v[28:29], v[26:27], v[30:31] op_sel:[0,1] op_sel_hi:[1,0]
	v_pk_mul_f32 v[26:27], v[26:27], v[30:31]
	v_and_b32_e32 v30, 0xffff0000, v19
	v_lshlrev_b32_e32 v46, 16, v18
	v_and_b32_e32 v19, 0xffff0000, v22
	v_and_b32_e32 v18, 0xffff0000, v18
	v_and_b32_e32 v31, 0xffff0000, v23
	v_pk_mul_f32 v[46:47], v[46:47], s[48:49] op_sel_hi:[1,0]
	v_pk_mul_f32 v[22:23], v[18:19], s[48:49] op_sel_hi:[1,0]
	v_pk_mul_f32 v[48:49], v[46:47], v[42:43] op_sel:[0,1] op_sel_hi:[1,0]
	v_pk_mul_f32 v[42:43], v[46:47], v[42:43]
	v_pk_mul_f32 v[18:19], v[22:23], v[40:41] op_sel:[0,1] op_sel_hi:[1,0]
	v_pk_mul_f32 v[22:23], v[22:23], v[40:41]
	v_mov_b32_e32 v40, v42
	v_mov_b32_e32 v41, v22
	v_mov_b32_e32 v22, v43
	v_pk_add_f32 v[22:23], v[40:41], v[22:23]
	v_lshlrev_b32_e32 v41, 16, v21
	v_lshlrev_b32_e32 v40, 16, v17
	v_pk_mul_f32 v[40:41], v[40:41], s[48:49] op_sel_hi:[1,0]
	v_mov_b32_e32 v46, v48
	v_mov_b32_e32 v47, v18
	v_mov_b32_e32 v18, v49
	v_pk_mul_f32 v[42:43], v[40:41], v[32:33] op_sel:[0,1] op_sel_hi:[1,0]
	v_pk_mul_f32 v[40:41], v[40:41], v[32:33]
	v_and_b32_e32 v33, 0xffff0000, v21
	v_and_b32_e32 v32, 0xffff0000, v17
	v_pk_add_f32 v[18:19], v[46:47], v[18:19] neg_lo:[0,1] neg_hi:[0,1]
	v_pk_mul_f32 v[46:47], v[32:33], s[48:49] op_sel_hi:[1,0]
	v_mov_b32_e32 v48, v42
	v_pk_mul_f32 v[32:33], v[46:47], v[34:35] op_sel:[0,1] op_sel_hi:[1,0]
	v_pk_mul_f32 v[34:35], v[46:47], v[34:35]
	v_mov_b32_e32 v49, v32
	v_mov_b32_e32 v32, v43
	v_mov_b32_e32 v42, v40
	v_mov_b32_e32 v43, v34
	v_mov_b32_e32 v34, v41
	v_lshlrev_b32_e32 v41, 16, v20
	v_lshlrev_b32_e32 v40, 16, v16
	v_and_b32_e32 v17, 0xffff0000, v20
	v_and_b32_e32 v16, 0xffff0000, v16
	v_pk_mul_f32 v[40:41], v[40:41], s[48:49] op_sel_hi:[1,0]
	v_pk_mul_f32 v[20:21], v[16:17], s[48:49] op_sel_hi:[1,0]
	v_pk_add_f32 v[34:35], v[42:43], v[34:35]
	v_pk_mul_f32 v[42:43], v[40:41], v[38:39] op_sel:[0,1] op_sel_hi:[1,0]
	v_pk_mul_f32 v[38:39], v[40:41], v[38:39]
	v_pk_mul_f32 v[16:17], v[20:21], v[36:37] op_sel:[0,1] op_sel_hi:[1,0]
	v_pk_mul_f32 v[20:21], v[20:21], v[36:37]
	v_mov_b32_e32 v36, v38
	v_mov_b32_e32 v37, v20
	v_mov_b32_e32 v20, v39
	v_pk_add_f32 v[20:21], v[36:37], v[20:21]
	v_lshlrev_b32_e32 v36, 16, v12
	v_and_b32_e32 v37, 0xffff0000, v12
	v_lshlrev_b32_e32 v12, 16, v13
	v_and_b32_e32 v13, 0xffff0000, v13
	v_pk_mul_f32 v[12:13], v[12:13], s[48:49] op_sel_hi:[1,0]
	v_lshlrev_b32_e32 v38, 16, v14
	v_cvt_pk_bf16_f32 v65, v12, v13
	v_lshlrev_b32_e32 v12, 16, v8
	v_and_b32_e32 v13, 0xffff0000, v8
	v_lshlrev_b32_e32 v8, 16, v9
	v_and_b32_e32 v9, 0xffff0000, v9
	v_pk_mul_f32 v[8:9], v[8:9], s[48:49] op_sel_hi:[1,0]
	v_and_b32_e32 v39, 0xffff0000, v14
	v_cvt_pk_bf16_f32 v69, v8, v9
	v_lshlrev_b32_e32 v8, 16, v4
	v_and_b32_e32 v9, 0xffff0000, v4
	v_lshlrev_b32_e32 v4, 16, v5
	v_and_b32_e32 v5, 0xffff0000, v5
	v_lshlrev_b32_e32 v14, 16, v15
	v_and_b32_e32 v15, 0xffff0000, v15
	v_pk_mul_f32 v[4:5], v[4:5], s[48:49] op_sel_hi:[1,0]
	s_mov_b32 s16, 0x2aaaaaab
	v_pk_mul_f32 v[14:15], v[14:15], s[48:49] op_sel_hi:[1,0]
	v_cvt_pk_bf16_f32 v73, v4, v5
	v_mul_hi_i32 v4, v160, s16
	v_cvt_pk_bf16_f32 v67, v14, v15
	v_lshlrev_b32_e32 v14, 16, v10
	v_and_b32_e32 v15, 0xffff0000, v10
; DI void phase_attn(const Params& p, int hf, bool skipctx, char* smem, int& rot) {
;     ...
;     const int kr0 = tid / 12, kc0 = tid - kr0 * 12, kr1 = (tid + 512) / 12, kc1 = (tid + 512) - kr1 * 12, kr2 = (tid + 1024) / 12, kc2 = (tid + 1024) - kr2 * 12;
;     const int vr0 = tid >> 4, vr1 = (tid + 512) >> 4, vc = tid & 15;
;     ...
;     __syncthreads();
;     ATT_LOAD(ak0, ak1, ak2, av0, av1, 0);
;     ATT_LOAD(bk0, bk1, bk2, bv0, bv1, 1);
	v_lshlrev_b32_e32 v10, 16, v11
	v_and_b32_e32 v11, 0xffff0000, v11
	v_lshrrev_b32_e32 v5, 31, v4
	v_ashrrev_i32_e32 v4, 1, v4
	v_pk_mul_f32 v[10:11], v[10:11], s[48:49] op_sel_hi:[1,0]
	v_add_u32_e32 v45, v4, v5
	v_cvt_pk_bf16_f32 v71, v10, v11
	v_lshlrev_b32_e32 v10, 16, v6
	v_and_b32_e32 v11, 0xffff0000, v6
	v_lshlrev_b32_e32 v6, 16, v7
	v_and_b32_e32 v7, 0xffff0000, v7
	v_mad_u64_u32 v[4:5], s[38:39], v45, -12, v[160:161]
	v_add_u32_e32 v164, 0x200, v160
	v_pk_mul_f32 v[6:7], v[6:7], s[48:49] op_sel_hi:[1,0]
	v_mul_hi_i32 v5, v164, s16
	v_cvt_pk_bf16_f32 v75, v6, v7
	v_lshrrev_b32_e32 v6, 31, v5
	v_ashrrev_i32_e32 v5, 1, v5
	s_mul_i32 s15, s4, 0xcc000
	v_add_u32_e32 v5, v5, v6
	v_pk_mul_f32 v[38:39], v[38:39], s[48:49] op_sel_hi:[1,0]
	v_pk_mul_f32 v[14:15], v[14:15], s[48:49] op_sel_hi:[1,0]
	s_mul_hi_i32 s5, s4, 0xcc000
	s_add_u32 s26, s90, s15
	v_mad_u64_u32 v[6:7], s[38:39], v5, -12, v[164:165]
	v_add_u32_e32 v162, 0x400, v160
	v_cvt_pk_bf16_f32 v66, v38, v39
	v_cvt_pk_bf16_f32 v70, v14, v15
	v_pk_mul_f32 v[8:9], v[8:9], s[48:49] op_sel_hi:[1,0]
	v_pk_mul_f32 v[10:11], v[10:11], s[48:49] op_sel_hi:[1,0]
	s_addc_u32 s27, s91, s5
	v_mul_hi_i32 v7, v162, s16
	v_lshlrev_b32_e32 v14, 3, v4
	v_lshlrev_b32_e32 v38, 3, v6
	v_pk_mul_f32 v[36:37], v[36:37], s[48:49] op_sel_hi:[1,0]
	v_pk_mul_f32 v[12:13], v[12:13], s[48:49] op_sel_hi:[1,0]
	v_cvt_pk_bf16_f32 v72, v8, v9
	v_cvt_pk_bf16_f32 v74, v10, v11
	v_lshrrev_b32_e32 v8, 31, v7
	v_ashrrev_i32_e32 v7, 1, v7
	v_mov_b64_e32 v[10:11], s[26:27]
	v_ashrrev_i32_e32 v15, 31, v14
	v_ashrrev_i32_e32 v39, 31, v38
	v_cvt_pk_bf16_f32 v64, v36, v37
	v_cvt_pk_bf16_f32 v68, v12, v13
	v_add_u32_e32 v7, v7, v8
	v_mad_i64_i32 v[12:13], s[26:27], v45, s17, v[10:11]
	v_lshlrev_b64 v[14:15], 1, v[14:15]
	v_mad_i64_i32 v[36:37], s[26:27], v5, s17, v[10:11]
	v_lshlrev_b64 v[38:39], 1, v[38:39]
	v_mad_u64_u32 v[8:9], s[38:39], v7, -12, v[162:163]
	v_lshl_add_u64 v[12:13], v[12:13], 0, v[14:15]
	v_lshl_add_u64 v[36:37], v[36:37], 0, v[38:39]
	s_barrier
	v_lshlrev_b32_e32 v36, 3, v8
	s_mul_i32 s15, s4, 0x88000
	v_readlane_b32 s36, v252, 5
	v_ashrrev_i32_e32 v37, 31, v36
	s_mul_hi_i32 s5, s4, 0x88000
	v_readlane_b32 s37, v252, 6
	s_add_u32 s36, s36, s15
	v_mad_i64_i32 v[12:13], s[26:27], v7, s17, v[10:11]
	v_lshlrev_b64 v[36:37], 1, v[36:37]
	s_addc_u32 s37, s37, s5
	v_lshl_add_u64 v[12:13], v[12:13], 0, v[36:37]
	v_mov_b32_e32 v40, v42
	v_mov_b32_e32 v41, v16
	v_mov_b32_e32 v16, v43
	v_ashrrev_i32_e32 v9, 4, v160
	v_ashrrev_i32_e32 v50, 4, v164
	v_mov_b64_e32 v[12:13], s[36:37]
	s_movk_i32 s16, 0x2200
	v_lshlrev_b32_e32 v165, 4, v160
	v_cvt_pk_bf16_f32 v100, v20, v21
	v_add_u32_e32 v20, 0x80, v5
	v_pk_add_f32 v[16:17], v[40:41], v[16:17] neg_lo:[0,1] neg_hi:[0,1]
	v_mad_i64_i32 v[40:41], s[26:27], v9, s16, v[12:13]
	v_and_b32_e32 v42, 0xf0, v165
	v_mov_b32_e32 v43, v221
	v_mad_i64_i32 v[12:13], s[26:27], v50, s16, v[12:13]
	v_cvt_pk_bf16_f32 v98, v18, v19
	v_cvt_pk_bf16_f32 v102, v22, v23
	v_add_u32_e32 v18, 0x80, v45
	v_mad_i64_i32 v[20:21], s[26:27], v20, s17, v[10:11]
	v_add_u32_e32 v22, 0x80, v7
	v_lshl_add_u64 v[40:41], v[40:41], 0, v[42:43]
	v_lshl_add_u64 v[12:13], v[12:13], 0, v[42:43]
	v_mad_i64_i32 v[18:19], s[26:27], v18, s17, v[10:11]
	v_lshl_add_u64 v[20:21], v[20:21], 0, v[38:39]
	v_mad_i64_i32 v[10:11], s[26:27], v22, s17, v[10:11]
	v_lshl_add_u64 v[18:19], v[18:19], 0, v[14:15]
	v_lshl_add_u64 v[10:11], v[10:11], 0, v[36:37]
	v_lshlrev_b32_e32 v46, 16, v0
	v_and_b32_e32 v47, 0xffff0000, v0
	v_lshlrev_b32_e32 v0, 16, v1
	v_and_b32_e32 v1, 0xffff0000, v1
	v_pk_mul_f32 v[30:31], v[30:31], s[48:49] op_sel_hi:[1,0]
	v_pk_add_f32 v[32:33], v[48:49], v[32:33] neg_lo:[0,1] neg_hi:[0,1]
	v_pk_mul_f32 v[0:1], v[0:1], s[48:49] op_sel_hi:[1,0]
	v_lshlrev_b32_e32 v48, 16, v2
	v_and_b32_e32 v49, 0xffff0000, v2
	v_lshlrev_b32_e32 v2, 16, v3
	v_and_b32_e32 v3, 0xffff0000, v3
	v_pk_mul_f32 v[2:3], v[2:3], s[48:49] op_sel_hi:[1,0]
	v_cvt_pk_bf16_f32 v89, v0, v1
	v_pk_mul_f32 v[0:1], v[30:31], v[24:25] op_sel:[0,1] op_sel_hi:[1,0]
	v_cvt_pk_bf16_f32 v91, v2, v3
	v_mov_b32_e32 v2, v28
	v_mov_b32_e32 v3, v0
	v_mov_b32_e32 v0, v29
	v_pk_add_f32 v[0:1], v[2:3], v[0:1] neg_lo:[0,1] neg_hi:[0,1]
	v_pk_mul_f32 v[2:3], v[30:31], v[24:25]
	v_mul_lo_u32 v10, v45, s97
	v_mov_b32_e32 v24, v26
	v_mov_b32_e32 v25, v2
	v_mov_b32_e32 v2, v27
	v_add_u32_e32 v10, 0, v10
	v_lshlrev_b32_e32 v4, 4, v4
	v_pk_add_f32 v[2:3], v[24:25], v[2:3]
	v_add_u32_e32 v176, v10, v4
	v_mul_lo_u32 v4, v5, s97
	v_cvt_pk_bf16_f32 v103, v2, v3
	v_mad_i64_i32 v[2:3], s[26:27], v5, s17, 0
	v_add_u32_e32 v4, 0, v4
	v_lshlrev_b32_e32 v5, 4, v6
	v_add_u32_e32 v177, v4, v5
	v_mul_lo_u32 v4, v7, s97
; DI f32x16 zero16() { f32x16 z; for (int i = 0; i < 16; ++i) z[i] = 0.f; return z; }
; DI void phase_attn(const Params& p, int hf, bool skipctx, char* smem, int& rot) {
;     ...
;     f32x16 o[2]; o[0] = zero16(); o[1] = zero16();
;     float m_run = -1e30f, l_run = 0.f;
;     uint4 ak0, ak1, ak2, av0, av1, bk0, bk1, bk2, bv0, bv1;
;     const int kr0 = tid / 12, kc0 = tid - kr0 * 12, kr1 = (tid + 512) / 12, kc1 = (tid + 512) - kr1 * 12, kr2 = (tid + 1024) / 12, kc2 = (tid + 1024) - kr2 * 12;
;     const int vr0 = tid >> 4, vr1 = (tid + 512) >> 4, vc = tid & 15;
;     ...
;     ATT_WRITE(ak0, ak1, ak2, av0, av1, 0);
;     __syncthreads();
	v_add_u32_e32 v4, 0, v4
	v_lshlrev_b32_e32 v5, 4, v8
	s_movk_i32 s20, 0x108
	v_cvt_pk_bf16_f32 v96, v16, v17
	v_cvt_pk_bf16_f32 v99, v0, v1
	v_mad_i64_i32 v[0:1], s[26:27], v45, s17, 0
	v_mad_i64_i32 v[16:17], s[26:27], v7, s17, 0
	v_add_u32_e32 v178, v4, v5
	v_mul_lo_u32 v4, v9, s20
	v_add_u32_e32 v5, 0, v4
	s_movk_i32 s26, 0x6800
	v_add3_u32 v179, v5, v42, s26
	v_mul_lo_u32 v5, v50, s20
	v_add_u32_e32 v6, 0, v5
	v_add3_u32 v180, v6, v42, s26
	v_or_b32_e32 v181, 32, v161
	v_or_b32_e32 v182, 64, v161
	v_or_b32_e32 v183, 0x60, v161
	v_readlane_b32 s26, v254, 35
	v_mul_u32_u24_e32 v19, 0x108, v44
	v_mad_u32_u24 v18, v44, s97, 0
	v_add_u32_e32 v21, s26, v4
	v_add_u32_e32 v22, s26, v5
	v_add_u32_e32 v23, s26, v161
	v_add_u32_e32 v24, s26, v181
	v_mov_b32_e32 v4, s26
	v_add_u32_e32 v25, s26, v182
	v_add_u32_e32 v26, s26, v183
	v_readlane_b32 s26, v254, 36
	v_mad_u32_u24 v184, v44, s20, v4
	v_add_u32_e32 v20, 0, v161
	v_add_u32_e32 v27, s26, v161
	v_add_u32_e32 v28, s26, v181
	v_mov_b32_e32 v4, s26
	v_add_u32_e32 v29, s26, v182
	v_add_u32_e32 v30, s26, v183
	s_add_u32 s26, s15, 0x1a49c300
	s_addc_u32 s27, s5, 0
	v_mad_u32_u24 v185, v44, s20, v4
	v_mov_b64_e32 v[4:5], s[26:27]
	v_mad_i64_i32 v[166:167], s[26:27], v9, s16, v[4:5]
	v_mad_i64_i32 v[168:169], s[26:27], v50, s16, v[4:5]
	v_mad_i64_i32 v[4:5], s[26:27], s4, v231, v[16:17]
	v_mad_i64_i32 v[2:3], s[26:27], s4, v231, v[2:3]
	v_mad_i64_i32 v[0:1], s[4:5], s4, v231, v[0:1]
	v_lshl_add_u64 v[174:175], v[0:1], 0, v[14:15]
	v_mov_b32_e32 v14, v221
	v_mov_b32_e32 v15, v221
	v_add_u32_e32 v186, v21, v42
	v_add_u32_e32 v187, v22, v42
	v_add_u32_e32 v188, v23, v19
	v_add_u32_e32 v16, v24, v19
	v_add_u32_e32 v17, v25, v19
	v_add_u32_e32 v21, v26, v19
	v_add_u32_e32 v22, v28, v19
	v_add_u32_e32 v23, v29, v19
	v_add_u32_e32 v24, v30, v19
	v_pk_mul_f32 v[46:47], v[46:47], s[48:49] op_sel_hi:[1,0]
	v_pk_mul_f32 v[48:49], v[48:49], s[48:49] op_sel_hi:[1,0]
	v_lshl_add_u64 v[170:171], v[4:5], 0, v[36:37]
	v_lshl_add_u64 v[172:173], v[2:3], 0, v[38:39]
	v_mov_b32_e32 v0, v221
	v_mov_b32_e32 v1, v221
	v_mov_b32_e32 v2, v221
	v_mov_b32_e32 v3, v221
	v_mov_b32_e32 v4, v221
	v_mov_b32_e32 v5, v221
	v_mov_b32_e32 v6, v221
	v_mov_b32_e32 v7, v221
	v_mov_b32_e32 v8, v221
	v_mov_b32_e32 v9, v221
	v_mov_b32_e32 v10, v221
	v_mov_b32_e32 v11, v221
	v_mov_b32_e32 v12, v221
	v_mov_b32_e32 v13, v221
	v_add_u32_e32 v189, v27, v19
	v_add_u32_e32 v190, v18, v220
	v_add_u32_e32 v191, v20, v19
	v_add_u32_e32 v194, 0x2000, v16
	v_add_u32_e32 v204, 0x2000, v17
	v_add_u32_e32 v206, 0x2000, v21
	v_add_u32_e32 v208, 0x2000, v22
	v_add_u32_e32 v210, 0x2000, v23
	v_add_u32_e32 v211, 0x2000, v24
	v_mov_b64_e32 v[30:31], v[14:15]
	v_cvt_pk_bf16_f32 v88, v46, v47
	v_cvt_pk_bf16_f32 v90, v48, v49
	v_cvt_pk_bf16_f32 v97, v32, v33
	v_cvt_pk_bf16_f32 v101, v34, v35
	v_or_b32_e32 v166, v166, v42
	v_or_b32_e32 v168, v168, v42
	s_mov_b32 s4, 0
	v_mov_b32_e32 v212, 0xf149f2ca
	v_mov_b32_e32 v213, 0
	v_mov_b64_e32 v[28:29], v[12:13]
	v_mov_b64_e32 v[26:27], v[10:11]
	v_mov_b64_e32 v[24:25], v[8:9]
	v_mov_b64_e32 v[22:23], v[6:7]
	v_mov_b64_e32 v[20:21], v[4:5]
	v_mov_b64_e32 v[18:19], v[2:3]
	v_mov_b64_e32 v[16:17], v[0:1]
	v_and_b32_e32 v200, 15, v192
	v_lshrrev_b32_e32 v201, 4, v192
	v_mul_u32_u24_e32 v179, 0x110, v201
	v_lshrrev_b32_e32 v202, 1, v200
	v_lshl_add_u32 v179, v202, 5, v179
	v_and_b32_e32 v202, 1, v200
	v_lshl_add_u32 v179, v202, 3, v179
	v_add_u32_e32 v179, 0x6800, v179
	v_add_u32_e32 v180, 0x2200, v179
	v_add_u32_e32 v186, 0xac00, v179
	v_add_u32_e32 v187, 0xac00, v180
	v_and_b32_e32 v200, 31, v192
	v_bfe_u32 v201, v192, 5, 1
	v_mul_u32_u24_e32 v191, 0x110, v200
	v_lshl_add_u32 v191, v201, 4, v191
	v_add_u32_e32 v191, 0x6800, v191
	s_waitcnt vmcnt(9)
	ds_write_b128 v176, v[76:79]
	s_waitcnt vmcnt(8)
	ds_write_b128 v177, v[80:83]
	s_waitcnt vmcnt(7)
	ds_write_b128 v178, v[84:87]
	s_waitcnt vmcnt(6)
	ds_write_b64 v179, v[92:93] offset:0
	ds_write_b64 v179, v[94:95] offset:16
	s_waitcnt vmcnt(5)
	ds_write_b64 v179, v[104:105] offset:8704
	ds_write_b64 v179, v[106:107] offset:8720
	s_waitcnt lgkmcnt(0)
	s_barrier
	v_mov_b32_e32 v194, v176
	v_mov_b32_e32 v204, v177
	v_mov_b32_e32 v206, v178
	v_mov_b32_e32 v208, v179
	v_mov_b32_e32 v210, v190
	v_mov_b32_e32 v211, v191
	v_mov_b32_e32 v220, 0xf149f2ca
	v_mov_b32_e32 v176, 0
	v_mov_b32_e32 v177, 0
	v_mov_b32_e32 v178, 0
	v_mov_b32_e32 v179, 0
	v_mov_b32_e32 v180, 0
	v_mov_b32_e32 v181, 0
	v_mov_b32_e32 v182, 0
	v_mov_b32_e32 v183, 0
	v_mov_b32_e32 v184, 0
	v_mov_b32_e32 v185, 0
	v_mov_b32_e32 v186, 0
	v_mov_b32_e32 v187, 0
	v_mov_b32_e32 v188, 0
	v_mov_b32_e32 v189, 0
	v_mov_b32_e32 v190, 0
	v_mov_b32_e32 v191, 0

; DI float bflo(unsigned u) { return __uint_as_float(u << 16); }
; DI float bfhi(unsigned u) { return __uint_as_float(u & 0xffff0000u); }
; DI f32x16 zero16() { f32x16 z; for (int i = 0; i < 16; ++i) z[i] = 0.f; return z; }
; DI void phase_attn(const Params& p, int hf, bool skipctx, char* smem, int& rot) {
;     ...
;       for (int ks = 0; ks < 6; ++ks) qu[ks] = *(const uint4*)(Qb + tq * 768 + head * 96 + ks * 16 + h * 8);
; #pragma unroll
;       for (int ks = 0; ks < 4; ++ks) {
;         const uint4 u = qu[ks];
;         qf[ks] = pack8(bflo(u.x) * QSCALE, bfhi(u.x) * QSCALE, bflo(u.y) * QSCALE, bfhi(u.y) * QSCALE, bflo(u.z) * QSCALE, bfhi(u.z) * QSCALE, bflo(u.w) * QSCALE, bfhi(u.w) * QSCALE);
;       }
;       const unsigned a1[4] = {qu[4].x, qu[4].y, qu[4].z, qu[4].w}, a2[4] = {qu[5].x, qu[5].y, qu[5].z, qu[5].w};
;       float o1[8], o2[8];
;       const int sq_ = s0 + w * 32 + r;
; #pragma unroll
;       for (int e = 0; e < 8; ++e) {
;         const float x1 = ((e & 1) ? bfhi(a1[e >> 1]) : bflo(a1[e >> 1])) * QSCALE;
;         const float x2 = ((e & 1) ? bfhi(a2[e >> 1]) : bflo(a2[e >> 1])) * QSCALE;
;         float cs = 1.f, sn = 0.f;
;         if (sq_ >= LC) { cs = axc[(sq_ - LC) * 16 + 8 * h + e]; sn = axs[(sq_ - LC) * 16 + 8 * h + e]; }
;         o1[e] = x1 * cs - x2 * sn; o2[e] = x1 * sn + x2 * cs;
;       }
;       qf[4] = pack8(o1[0], o1[1], o1[2], o1[3], o1[4], o1[5], o1[6], o1[7]);
;       qf[5] = pack8(o2[0], o2[1], o2[2], o2[3], o2[4], o2[5], o2[6], o2[7]);
;     }
;     const bf16_t* Kg = Kb + (size_t)(bl * 8 + head) * S * 96;
;     const bf16_t* Vg = VTb + (size_t)(bl * 8 + head) * 64 * S;
;     f32x16 o[2]; o[0] = zero16(); o[1] = zero16();
;     float m_run = -1e30f, l_run = 0.f;
;     uint4 ak0, ak1, ak2, av0, av1, bk0, bk1, bk2, bv0, bv1;
;     const int kr0 = tid / 12, kc0 = tid - kr0 * 12, kr1 = (tid + 512) / 12, kc1 = (tid + 512) - kr1 * 12, kr2 = (tid + 1024) / 12, kc2 = (tid + 1024) - kr2 * 12;
;     const int vr0 = tid >> 4, vr1 = (tid + 512) >> 4, vc = tid & 15;
.LBB0_1059:
	s_or_b64 exec, exec, s[26:27]
	v_mov_b32_e32 v128, s4
	v_mov_b32_e32 v129, 0xcc000
	v_mov_b32_e32 v130, s90
	v_mov_b32_e32 v131, s91
	v_readlane_b32 s100, v252, 5
	v_readlane_b32 s101, v252, 6
	v_mad_u64_u32 v[132:133], vcc, v128, v129, v[130:131]
	v_mov_b32_e32 v129, 0x88000
	v_mov_b32_e32 v157, 0
	v_mov_b32_e32 v130, s100
	v_mov_b32_e32 v131, s101
	v_mov_b32_e32 v138, 0x2aaaaaab
	v_mad_u64_u32 v[134:135], vcc, v128, v129, v[130:131]
	v_mov_b32_e32 v136, v160
	v_mul_hi_u32 v137, v136, v138
	v_lshrrev_b32_e32 v137, 1, v137
	v_mul_u32_u24_e32 v139, 12, v137
	v_sub_u32_e32 v139, v136, v139
	v_mul_u32_u24_e32 v137, 0xc0, v137
	v_lshl_add_u32 v156, v139, 4, v137
	v_lshl_add_u64 v[140:141], v[132:133], 0, v[156:157]
	v_add_u32_e32 v136, 0x200, v160
	v_mul_hi_u32 v137, v136, v138
	v_lshrrev_b32_e32 v137, 1, v137
	v_mul_u32_u24_e32 v139, 12, v137
	v_sub_u32_e32 v139, v136, v139
	v_mul_u32_u24_e32 v137, 0xc0, v137
	v_lshl_add_u32 v156, v139, 4, v137
	v_lshl_add_u64 v[142:143], v[132:133], 0, v[156:157]
	v_add_u32_e32 v136, 0x400, v160
	v_mul_hi_u32 v137, v136, v138
	v_lshrrev_b32_e32 v137, 1, v137
	v_mul_u32_u24_e32 v139, 12, v137
	v_sub_u32_e32 v139, v136, v139
	v_mul_u32_u24_e32 v137, 0xc0, v137
	v_lshl_add_u32 v156, v139, 4, v137
	v_lshl_add_u64 v[144:145], v[132:133], 0, v[156:157]
	v_lshrrev_b32_e32 v136, 4, v160
	v_and_b32_e32 v139, 15, v160
	v_lshlrev_b32_e32 v139, 4, v139
	v_mov_b32_e32 v137, 0x2200
	v_mad_u32_u24 v156, v136, v137, v139
	v_lshl_add_u64 v[146:147], v[134:135], 0, v[156:157]
	v_mov_b32_e32 v156, 0x44000
	v_lshl_add_u64 v[148:149], v[146:147], 0, v[156:157]
	global_load_dwordx4 v[76:79], v[140:141], off
	global_load_dwordx4 v[80:83], v[142:143], off
	global_load_dwordx4 v[84:87], v[144:145], off
	global_load_dwordx4 v[92:95], v[146:147], off
	global_load_dwordx4 v[104:107], v[148:149], off
	v_mov_b32_e32 v156, 0x6000
	v_lshl_add_u64 v[150:151], v[142:143], 0, v[156:157]
	v_lshl_add_u64 v[152:153], v[144:145], 0, v[156:157]
	v_lshl_add_u64 v[154:155], v[140:141], 0, v[156:157]
	global_load_dwordx4 v[108:111], v[150:151], off
	global_load_dwordx4 v[116:119], v[152:153], off
	global_load_dwordx4 v[120:123], v[146:147], off offset:256
	global_load_dwordx4 v[112:115], v[154:155], off
	global_load_dwordx4 v[124:127], v[148:149], off offset:256
	s_waitcnt vmcnt(10)
	v_lshlrev_b32_e32 v27, 16, v23
	v_lshlrev_b32_e32 v26, 16, v19
	v_pk_mul_f32 v[26:27], v[26:27], s[48:49] op_sel_hi:[1,0]
	v_lshlrev_b32_e32 v47, 16, v22
	v_pk_mul_f32 v[28:29], v[26:27], v[30:31] op_sel:[0,1] op_sel_hi:[1,0]
	v_pk_mul_f32 v[26:27], v[26:27], v[30:31]
	v_and_b32_e32 v30, 0xffff0000, v19
	v_lshlrev_b32_e32 v46, 16, v18
	v_and_b32_e32 v19, 0xffff0000, v22
	v_and_b32_e32 v18, 0xffff0000, v18
	v_and_b32_e32 v31, 0xffff0000, v23
	v_pk_mul_f32 v[46:47], v[46:47], s[48:49] op_sel_hi:[1,0]
	v_pk_mul_f32 v[22:23], v[18:19], s[48:49] op_sel_hi:[1,0]
	v_pk_mul_f32 v[48:49], v[46:47], v[42:43] op_sel:[0,1] op_sel_hi:[1,0]
	v_pk_mul_f32 v[42:43], v[46:47], v[42:43]
	v_pk_mul_f32 v[18:19], v[22:23], v[40:41] op_sel:[0,1] op_sel_hi:[1,0]
	v_pk_mul_f32 v[22:23], v[22:23], v[40:41]
	v_mov_b32_e32 v40, v42
	v_mov_b32_e32 v41, v22
	v_mov_b32_e32 v22, v43
	v_pk_add_f32 v[22:23], v[40:41], v[22:23]
	v_lshlrev_b32_e32 v41, 16, v21
	v_lshlrev_b32_e32 v40, 16, v17
	v_pk_mul_f32 v[40:41], v[40:41], s[48:49] op_sel_hi:[1,0]
	v_mov_b32_e32 v46, v48
	v_mov_b32_e32 v47, v18
	v_mov_b32_e32 v18, v49
	v_pk_mul_f32 v[42:43], v[40:41], v[32:33] op_sel:[0,1] op_sel_hi:[1,0]
	v_pk_mul_f32 v[40:41], v[40:41], v[32:33]
	v_and_b32_e32 v33, 0xffff0000, v21
	v_and_b32_e32 v32, 0xffff0000, v17
	v_pk_add_f32 v[18:19], v[46:47], v[18:19] neg_lo:[0,1] neg_hi:[0,1]
	v_pk_mul_f32 v[46:47], v[32:33], s[48:49] op_sel_hi:[1,0]
	v_mov_b32_e32 v48, v42
	v_pk_mul_f32 v[32:33], v[46:47], v[34:35] op_sel:[0,1] op_sel_hi:[1,0]
	v_pk_mul_f32 v[34:35], v[46:47], v[34:35]
	v_mov_b32_e32 v49, v32
	v_mov_b32_e32 v32, v43
	v_mov_b32_e32 v42, v40
	v_mov_b32_e32 v43, v34
	v_mov_b32_e32 v34, v41
	v_lshlrev_b32_e32 v41, 16, v20
	v_lshlrev_b32_e32 v40, 16, v16
	v_and_b32_e32 v17, 0xffff0000, v20
	v_and_b32_e32 v16, 0xffff0000, v16
	v_pk_mul_f32 v[40:41], v[40:41], s[48:49] op_sel_hi:[1,0]
	v_pk_mul_f32 v[20:21], v[16:17], s[48:49] op_sel_hi:[1,0]
	v_pk_add_f32 v[34:35], v[42:43], v[34:35]
	v_pk_mul_f32 v[42:43], v[40:41], v[38:39] op_sel:[0,1] op_sel_hi:[1,0]
	v_pk_mul_f32 v[38:39], v[40:41], v[38:39]
	v_pk_mul_f32 v[16:17], v[20:21], v[36:37] op_sel:[0,1] op_sel_hi:[1,0]
	v_pk_mul_f32 v[20:21], v[20:21], v[36:37]
	v_mov_b32_e32 v36, v38
	v_mov_b32_e32 v37, v20
	v_mov_b32_e32 v20, v39
	v_pk_add_f32 v[20:21], v[36:37], v[20:21]
	v_lshlrev_b32_e32 v36, 16, v12
	v_and_b32_e32 v37, 0xffff0000, v12
	v_lshlrev_b32_e32 v12, 16, v13
	v_and_b32_e32 v13, 0xffff0000, v13
	v_pk_mul_f32 v[12:13], v[12:13], s[48:49] op_sel_hi:[1,0]
	v_lshlrev_b32_e32 v38, 16, v14
	v_cvt_pk_bf16_f32 v65, v12, v13
	v_lshlrev_b32_e32 v12, 16, v8
	v_and_b32_e32 v13, 0xffff0000, v8
	v_lshlrev_b32_e32 v8, 16, v9
	v_and_b32_e32 v9, 0xffff0000, v9
	v_pk_mul_f32 v[8:9], v[8:9], s[48:49] op_sel_hi:[1,0]
	v_and_b32_e32 v39, 0xffff0000, v14
	v_cvt_pk_bf16_f32 v69, v8, v9
	v_lshlrev_b32_e32 v8, 16, v4
	v_and_b32_e32 v9, 0xffff0000, v4
	v_lshlrev_b32_e32 v4, 16, v5
	v_and_b32_e32 v5, 0xffff0000, v5
	v_lshlrev_b32_e32 v14, 16, v15
	v_and_b32_e32 v15, 0xffff0000, v15
	v_pk_mul_f32 v[4:5], v[4:5], s[48:49] op_sel_hi:[1,0]
	s_mov_b32 s29, 0x2aaaaaab
	v_pk_mul_f32 v[14:15], v[14:15], s[48:49] op_sel_hi:[1,0]
	v_cvt_pk_bf16_f32 v73, v4, v5
	v_mul_hi_i32 v4, v160, s29
	v_cvt_pk_bf16_f32 v67, v14, v15
	v_lshlrev_b32_e32 v14, 16, v10
	v_and_b32_e32 v15, 0xffff0000, v10
; DI void phase_attn(const Params& p, int hf, bool skipctx, char* smem, int& rot) {
;     ...
;     const int kr0 = tid / 12, kc0 = tid - kr0 * 12, kr1 = (tid + 512) / 12, kc1 = (tid + 512) - kr1 * 12, kr2 = (tid + 1024) / 12, kc2 = (tid + 1024) - kr2 * 12;
;     const int vr0 = tid >> 4, vr1 = (tid + 512) >> 4, vc = tid & 15;
;     ...
;     __syncthreads();
;     ATT_LOAD(ak0, ak1, ak2, av0, av1, 0);
;     ATT_LOAD(bk0, bk1, bk2, bv0, bv1, 1);
	v_lshlrev_b32_e32 v10, 16, v11
	v_and_b32_e32 v11, 0xffff0000, v11
	v_lshrrev_b32_e32 v5, 31, v4
	v_ashrrev_i32_e32 v4, 1, v4
	v_pk_mul_f32 v[10:11], v[10:11], s[48:49] op_sel_hi:[1,0]
	v_add_u32_e32 v45, v4, v5
	v_cvt_pk_bf16_f32 v71, v10, v11
	v_lshlrev_b32_e32 v10, 16, v6
	v_and_b32_e32 v11, 0xffff0000, v6
	v_lshlrev_b32_e32 v6, 16, v7
	v_and_b32_e32 v7, 0xffff0000, v7
	v_mad_u64_u32 v[4:5], s[38:39], v45, -12, v[160:161]
	v_add_u32_e32 v164, 0x200, v160
	v_pk_mul_f32 v[6:7], v[6:7], s[48:49] op_sel_hi:[1,0]
	v_mul_hi_i32 v5, v164, s29
	v_cvt_pk_bf16_f32 v75, v6, v7
	v_lshrrev_b32_e32 v6, 31, v5
	v_ashrrev_i32_e32 v5, 1, v5
	s_mul_i32 s15, s4, 0xcc000
	v_add_u32_e32 v5, v5, v6
	v_pk_mul_f32 v[38:39], v[38:39], s[48:49] op_sel_hi:[1,0]
	v_pk_mul_f32 v[14:15], v[14:15], s[48:49] op_sel_hi:[1,0]
	s_mul_hi_i32 s5, s4, 0xcc000
	s_add_u32 s26, s90, s15
	v_mad_u64_u32 v[6:7], s[38:39], v5, -12, v[164:165]
	v_add_u32_e32 v162, 0x400, v160
	v_cvt_pk_bf16_f32 v66, v38, v39
	v_cvt_pk_bf16_f32 v70, v14, v15
	v_pk_mul_f32 v[8:9], v[8:9], s[48:49] op_sel_hi:[1,0]
	v_pk_mul_f32 v[10:11], v[10:11], s[48:49] op_sel_hi:[1,0]
	s_addc_u32 s27, s91, s5
	v_mul_hi_i32 v7, v162, s29
	v_lshlrev_b32_e32 v14, 3, v4
	v_lshlrev_b32_e32 v38, 3, v6
	v_pk_mul_f32 v[36:37], v[36:37], s[48:49] op_sel_hi:[1,0]
	v_pk_mul_f32 v[12:13], v[12:13], s[48:49] op_sel_hi:[1,0]
	v_cvt_pk_bf16_f32 v72, v8, v9
	v_cvt_pk_bf16_f32 v74, v10, v11
	v_lshrrev_b32_e32 v8, 31, v7
	v_ashrrev_i32_e32 v7, 1, v7
	v_mov_b64_e32 v[10:11], s[26:27]
	v_ashrrev_i32_e32 v15, 31, v14
	v_ashrrev_i32_e32 v39, 31, v38
	v_cvt_pk_bf16_f32 v64, v36, v37
	v_cvt_pk_bf16_f32 v68, v12, v13
	v_add_u32_e32 v7, v7, v8
	v_mad_i64_i32 v[12:13], s[26:27], v45, s17, v[10:11]
	v_lshlrev_b64 v[14:15], 1, v[14:15]
	v_mad_i64_i32 v[36:37], s[26:27], v5, s17, v[10:11]
	v_lshlrev_b64 v[38:39], 1, v[38:39]
	v_mad_u64_u32 v[8:9], s[38:39], v7, -12, v[162:163]
	v_lshl_add_u64 v[12:13], v[12:13], 0, v[14:15]
	v_lshl_add_u64 v[36:37], v[36:37], 0, v[38:39]
	s_barrier
	v_lshlrev_b32_e32 v36, 3, v8
	s_mul_i32 s15, s4, 0x88000
	v_readlane_b32 s36, v252, 5
	v_ashrrev_i32_e32 v37, 31, v36
	s_mul_hi_i32 s5, s4, 0x88000
	v_readlane_b32 s37, v252, 6
	s_add_u32 s36, s36, s15
	v_mad_i64_i32 v[12:13], s[26:27], v7, s17, v[10:11]
	v_lshlrev_b64 v[36:37], 1, v[36:37]
	s_addc_u32 s37, s37, s5
	v_lshl_add_u64 v[12:13], v[12:13], 0, v[36:37]
	v_mov_b32_e32 v40, v42
	v_mov_b32_e32 v41, v16
	v_mov_b32_e32 v16, v43
	v_ashrrev_i32_e32 v9, 4, v160
	v_ashrrev_i32_e32 v50, 4, v164
	v_mov_b64_e32 v[12:13], s[36:37]
	v_lshlrev_b32_e32 v165, 4, v160
	v_cvt_pk_bf16_f32 v100, v20, v21
	v_add_u32_e32 v20, 0x80, v5
	v_pk_add_f32 v[16:17], v[40:41], v[16:17] neg_lo:[0,1] neg_hi:[0,1]
	v_mad_i64_i32 v[40:41], s[26:27], v9, s16, v[12:13]
	v_and_b32_e32 v42, 0xf0, v165
	v_mov_b32_e32 v43, v221
	v_mad_i64_i32 v[12:13], s[26:27], v50, s16, v[12:13]
	v_cvt_pk_bf16_f32 v98, v18, v19
	v_cvt_pk_bf16_f32 v102, v22, v23
	v_add_u32_e32 v18, 0x80, v45
	v_mad_i64_i32 v[20:21], s[26:27], v20, s17, v[10:11]
	v_add_u32_e32 v22, 0x80, v7
	v_lshl_add_u64 v[40:41], v[40:41], 0, v[42:43]
	v_lshl_add_u64 v[12:13], v[12:13], 0, v[42:43]
	v_mad_i64_i32 v[18:19], s[26:27], v18, s17, v[10:11]
	v_lshl_add_u64 v[20:21], v[20:21], 0, v[38:39]
	v_mad_i64_i32 v[10:11], s[26:27], v22, s17, v[10:11]
	v_lshl_add_u64 v[18:19], v[18:19], 0, v[14:15]
	v_lshl_add_u64 v[10:11], v[10:11], 0, v[36:37]
	v_lshlrev_b32_e32 v46, 16, v0
	v_and_b32_e32 v47, 0xffff0000, v0
	v_lshlrev_b32_e32 v0, 16, v1
	v_and_b32_e32 v1, 0xffff0000, v1
	v_pk_mul_f32 v[30:31], v[30:31], s[48:49] op_sel_hi:[1,0]
	v_pk_add_f32 v[32:33], v[48:49], v[32:33] neg_lo:[0,1] neg_hi:[0,1]
	v_pk_mul_f32 v[0:1], v[0:1], s[48:49] op_sel_hi:[1,0]
	v_lshlrev_b32_e32 v48, 16, v2
	v_and_b32_e32 v49, 0xffff0000, v2
	v_lshlrev_b32_e32 v2, 16, v3
	v_and_b32_e32 v3, 0xffff0000, v3
	v_pk_mul_f32 v[2:3], v[2:3], s[48:49] op_sel_hi:[1,0]
	v_cvt_pk_bf16_f32 v89, v0, v1
	v_pk_mul_f32 v[0:1], v[30:31], v[24:25] op_sel:[0,1] op_sel_hi:[1,0]
	v_cvt_pk_bf16_f32 v91, v2, v3
	v_mov_b32_e32 v2, v28
	v_mov_b32_e32 v3, v0
	v_mov_b32_e32 v0, v29
	v_pk_add_f32 v[0:1], v[2:3], v[0:1] neg_lo:[0,1] neg_hi:[0,1]
	v_pk_mul_f32 v[2:3], v[30:31], v[24:25]
	v_mul_lo_u32 v10, v45, s97
	v_mov_b32_e32 v24, v26
	v_mov_b32_e32 v25, v2
	v_mov_b32_e32 v2, v27
	v_add_u32_e32 v10, 0, v10
	v_lshlrev_b32_e32 v4, 4, v4
	v_pk_add_f32 v[2:3], v[24:25], v[2:3]
	v_add_u32_e32 v176, v10, v4
	v_mul_lo_u32 v4, v5, s97
	v_cvt_pk_bf16_f32 v103, v2, v3
	v_mad_i64_i32 v[2:3], s[26:27], v5, s17, 0
	v_add_u32_e32 v4, 0, v4
	v_lshlrev_b32_e32 v5, 4, v6
	v_cvt_pk_bf16_f32 v96, v16, v17
	v_cvt_pk_bf16_f32 v99, v0, v1
; DI f32x16 zero16() { f32x16 z; for (int i = 0; i < 16; ++i) z[i] = 0.f; return z; }
; DI void phase_attn(const Params& p, int hf, bool skipctx, char* smem, int& rot) {
;     ...
;     f32x16 o[2]; o[0] = zero16(); o[1] = zero16();
;     float m_run = -1e30f, l_run = 0.f;
;     uint4 ak0, ak1, ak2, av0, av1, bk0, bk1, bk2, bv0, bv1;
;     const int kr0 = tid / 12, kc0 = tid - kr0 * 12, kr1 = (tid + 512) / 12, kc1 = (tid + 512) - kr1 * 12, kr2 = (tid + 1024) / 12, kc2 = (tid + 1024) - kr2 * 12;
;     const int vr0 = tid >> 4, vr1 = (tid + 512) >> 4, vc = tid & 15;
;     ...
;     ATT_WRITE(ak0, ak1, ak2, av0, av1, 0);
;     __syncthreads();
	v_mad_i64_i32 v[0:1], s[26:27], v45, s17, 0
	v_mad_i64_i32 v[16:17], s[26:27], v7, s17, 0
	v_add_u32_e32 v177, v4, v5
	v_mul_lo_u32 v4, v7, s97
	v_add_u32_e32 v4, 0, v4
	v_lshlrev_b32_e32 v5, 4, v8
	s_movk_i32 s26, 0x108
	v_add_u32_e32 v178, v4, v5
	v_mul_lo_u32 v4, v9, s26
	v_add_u32_e32 v5, 0, v4
	s_movk_i32 s27, 0x6800
	v_add3_u32 v179, v5, v42, s27
	v_mul_lo_u32 v5, v50, s26
	v_add_u32_e32 v6, 0, v5
	v_add3_u32 v180, v6, v42, s27
	v_or_b32_e32 v181, 32, v161
	v_or_b32_e32 v182, 64, v161
	v_or_b32_e32 v183, 0x60, v161
	v_readlane_b32 s27, v254, 35
	v_mul_u32_u24_e32 v19, 0x108, v44
	v_mad_u32_u24 v18, v44, s97, 0
	v_add_u32_e32 v21, s27, v4
	v_add_u32_e32 v22, s27, v5
	v_add_u32_e32 v23, s27, v161
	v_add_u32_e32 v24, s27, v181
	v_mov_b32_e32 v4, s27
	v_add_u32_e32 v25, s27, v182
	v_add_u32_e32 v26, s27, v183
	v_readlane_b32 s27, v254, 36
	v_mad_u32_u24 v184, v44, s26, v4
	v_add_u32_e32 v20, 0, v161
	v_mov_b32_e32 v4, s27
	v_mad_u32_u24 v185, v44, s26, v4
	s_add_u32 s26, s15, 0x1a49c300
	v_add_u32_e32 v27, s27, v161
	v_add_u32_e32 v28, s27, v181
	v_add_u32_e32 v29, s27, v182
	v_add_u32_e32 v30, s27, v183
	s_addc_u32 s27, s5, 0
	v_mov_b64_e32 v[4:5], s[26:27]
	v_mad_i64_i32 v[166:167], s[26:27], v9, s16, v[4:5]
	v_mad_i64_i32 v[168:169], s[26:27], v50, s16, v[4:5]
	v_mad_i64_i32 v[4:5], s[26:27], s4, v231, v[16:17]
	v_mad_i64_i32 v[2:3], s[26:27], s4, v231, v[2:3]
	v_mad_i64_i32 v[0:1], s[4:5], s4, v231, v[0:1]
	v_lshl_add_u64 v[174:175], v[0:1], 0, v[14:15]
	v_mov_b32_e32 v14, v221
	v_mov_b32_e32 v15, v221
	v_add_u32_e32 v186, v21, v42
	v_add_u32_e32 v187, v22, v42
	v_add_u32_e32 v188, v23, v19
	v_add_u32_e32 v16, v24, v19
	v_add_u32_e32 v17, v25, v19
	v_add_u32_e32 v21, v26, v19
	v_add_u32_e32 v22, v28, v19
	v_add_u32_e32 v23, v29, v19
	v_add_u32_e32 v24, v30, v19
	v_pk_mul_f32 v[46:47], v[46:47], s[48:49] op_sel_hi:[1,0]
	v_pk_mul_f32 v[48:49], v[48:49], s[48:49] op_sel_hi:[1,0]
	v_lshl_add_u64 v[170:171], v[4:5], 0, v[36:37]
	v_lshl_add_u64 v[172:173], v[2:3], 0, v[38:39]
	v_mov_b32_e32 v0, v221
	v_mov_b32_e32 v1, v221
	v_mov_b32_e32 v2, v221
	v_mov_b32_e32 v3, v221
	v_mov_b32_e32 v4, v221
	v_mov_b32_e32 v5, v221
	v_mov_b32_e32 v6, v221
	v_mov_b32_e32 v7, v221
	v_mov_b32_e32 v8, v221
	v_mov_b32_e32 v9, v221
	v_mov_b32_e32 v10, v221
	v_mov_b32_e32 v11, v221
	v_mov_b32_e32 v12, v221
	v_mov_b32_e32 v13, v221
	v_add_u32_e32 v189, v27, v19
	v_add_u32_e32 v190, v18, v220
	v_add_u32_e32 v191, v20, v19
	v_add_u32_e32 v194, 0x2000, v16
	v_add_u32_e32 v204, 0x2000, v17
	v_add_u32_e32 v206, 0x2000, v21
	v_add_u32_e32 v208, 0x2000, v22
	v_add_u32_e32 v210, 0x2000, v23
	v_add_u32_e32 v211, 0x2000, v24
	v_mov_b64_e32 v[30:31], v[14:15]
	v_cvt_pk_bf16_f32 v88, v46, v47
	v_cvt_pk_bf16_f32 v90, v48, v49
	v_cvt_pk_bf16_f32 v97, v32, v33
	v_cvt_pk_bf16_f32 v101, v34, v35
	v_or_b32_e32 v166, v166, v42
	v_or_b32_e32 v168, v168, v42
	s_mov_b32 s4, 0
	v_mov_b32_e32 v212, 0xf149f2ca
	v_mov_b32_e32 v213, 0
	v_mov_b64_e32 v[28:29], v[12:13]
	v_mov_b64_e32 v[26:27], v[10:11]
	v_mov_b64_e32 v[24:25], v[8:9]
	v_mov_b64_e32 v[22:23], v[6:7]
	v_mov_b64_e32 v[20:21], v[4:5]
	v_mov_b64_e32 v[18:19], v[2:3]
	v_mov_b64_e32 v[16:17], v[0:1]
	v_and_b32_e32 v200, 15, v192
	v_lshrrev_b32_e32 v201, 4, v192
	v_mul_u32_u24_e32 v179, 0x110, v201
	v_lshrrev_b32_e32 v202, 1, v200
	v_lshl_add_u32 v179, v202, 5, v179
	v_and_b32_e32 v202, 1, v200
	v_lshl_add_u32 v179, v202, 3, v179
	v_add_u32_e32 v179, 0x6800, v179
	v_add_u32_e32 v180, 0x2200, v179
	v_add_u32_e32 v186, 0xac00, v179
	v_add_u32_e32 v187, 0xac00, v180
	v_and_b32_e32 v200, 31, v192
	v_bfe_u32 v201, v192, 5, 1
	v_mul_u32_u24_e32 v191, 0x110, v200
	v_lshl_add_u32 v191, v201, 4, v191
	v_add_u32_e32 v191, 0x6800, v191
	s_waitcnt vmcnt(9)
	ds_write_b128 v176, v[76:79]
	s_waitcnt vmcnt(8)
	ds_write_b128 v177, v[80:83]
	s_waitcnt vmcnt(7)
	ds_write_b128 v178, v[84:87]
	s_waitcnt vmcnt(6)
	ds_write_b64 v179, v[92:93] offset:0
	ds_write_b64 v179, v[94:95] offset:16
	s_waitcnt vmcnt(5)
	ds_write_b64 v179, v[104:105] offset:8704
	ds_write_b64 v179, v[106:107] offset:8720
	s_waitcnt lgkmcnt(0)
	s_barrier
	v_mov_b32_e32 v194, v176
	v_mov_b32_e32 v204, v177
	v_mov_b32_e32 v206, v178
	v_mov_b32_e32 v208, v179
	v_mov_b32_e32 v210, v190
	v_mov_b32_e32 v211, v191
	v_mov_b32_e32 v220, 0xf149f2ca
	v_mov_b32_e32 v176, 0
	v_mov_b32_e32 v177, 0
	v_mov_b32_e32 v178, 0
	v_mov_b32_e32 v179, 0
	v_mov_b32_e32 v180, 0
	v_mov_b32_e32 v181, 0
	v_mov_b32_e32 v182, 0
	v_mov_b32_e32 v183, 0
	v_mov_b32_e32 v184, 0
	v_mov_b32_e32 v185, 0
	v_mov_b32_e32 v186, 0
	v_mov_b32_e32 v187, 0
	v_mov_b32_e32 v188, 0
	v_mov_b32_e32 v189, 0
	v_mov_b32_e32 v190, 0
	v_mov_b32_e32 v191, 0
